# no setprio + out-proj epilogue: row sums of squares reduced across the 4 column waves through LDS, one 32-lane atomic per wave at the end instead of 8 16-lane atomics per wave
# baseline (speedup 1.0000x reference)
.LBB0_1029:
	v_lshl_or_b32 v152, s30, 8, v186
	v_lshl_add_u32 v180, s28, 8, v184
	v_lshrrev_b32_e32 v246, 8, v236
	v_lshlrev_b32_e32 v246, 10, v246
	v_and_b32_e32 v247, 15, v236
	v_lshl_or_b32 v246, v247, 4, v246
	v_bfe_u32 v247, v236, 6, 2
	v_lshl_or_b32 v246, v247, 2, v246
	v_add_u32_e32 v246, 0x20400, v246
	s_ashr_i32 s21, s28, 4
	v_ashrrev_i32_e32 v153, 31, v152
	v_ashrrev_i32_e32 v181, 31, v180
	s_mul_hi_i32 s23, s21, 0x9000
	s_mul_i32 s21, s21, 0x9000
	v_lshl_add_u64 v[178:179], v[152:153], 1, s[80:81]
	v_lshlrev_b64 v[128:129], 11, v[180:181]
	s_add_u32 s28, s44, s21
	v_lshl_add_u64 v[128:129], v[178:179], 0, v[128:129]
	s_addc_u32 s29, s45, s23
	v_lshlrev_b64 v[130:131], 2, v[152:153]
	global_load_dwordx4 v[154:157], v[128:129], off
	v_lshl_add_u64 v[132:133], s[28:29], 0, v[130:131]
	s_add_u32 s28, s46, s21
	s_addc_u32 s29, s47, s23
	global_load_dwordx4 v[158:161], v[132:133], off
	global_load_dwordx4 v[162:165], v[132:133], off offset:16
	global_load_dwordx4 v[166:169], v[132:133], off offset:512
	global_load_dwordx4 v[192:195], v[132:133], off offset:528
	v_lshl_add_u64 v[132:133], s[28:29], 0, v[130:131]
	global_load_dwordx4 v[196:199], v[132:133], off
	global_load_dwordx4 v[200:203], v[132:133], off offset:16
	global_load_dwordx4 v[204:207], v[132:133], off offset:512
	global_load_dwordx4 v[208:211], v[132:133], off offset:528
	v_lshl_add_u64 v[130:131], s[12:13], 0, v[130:131]
	global_load_dwordx4 v[212:215], v[130:131], off
	global_load_dwordx4 v[216:219], v[130:131], off offset:16
	global_load_dwordx4 v[220:223], v[130:131], off offset:512
	global_load_dwordx4 v[224:227], v[130:131], off offset:528
	global_load_dwordx4 v[228:231], v[128:129], off offset:256
	v_or_b32_e32 v182, 16, v180
	v_ashrrev_i32_e32 v183, 31, v182
	v_lshlrev_b64 v[128:129], 10, v[180:181]
	v_lshlrev_b64 v[130:131], 11, v[182:183]
	v_lshl_add_u64 v[128:129], v[128:129], 0, v[152:153]
	v_lshl_add_u64 v[130:131], v[178:179], 0, v[130:131]
	v_lshlrev_b64 v[232:233], 1, v[128:129]
	global_load_dwordx4 v[132:135], v[130:131], off
	s_nop 0
	global_load_dwordx4 v[128:131], v[130:131], off offset:256
	v_lshl_add_u64 v[234:235], s[94:95], 0, v[232:233]
	s_waitcnt vmcnt(0)
	v_lshlrev_b32_e32 v238, 16, v154
	v_and_b32_e32 v239, 0xffff0000, v154
	v_lshlrev_b32_e32 v242, 16, v156
	v_and_b32_e32 v243, 0xffff0000, v156
	v_lshlrev_b32_e32 v244, 16, v157
	v_and_b32_e32 v245, 0xffff0000, v157
	v_pk_add_f32 v[174:175], v[158:159], 1.0 op_sel_hi:[1,0]
	v_pk_add_f32 v[172:173], v[164:165], 1.0 op_sel_hi:[1,0]
	v_pk_add_f32 v[170:171], v[162:163], 1.0 op_sel_hi:[1,0]
	v_lshlrev_b32_e32 v240, 16, v155
	v_and_b32_e32 v241, 0xffff0000, v155
	v_pk_add_f32 v[176:177], v[160:161], 1.0 op_sel_hi:[1,0]
	v_pk_fma_f32 v[238:239], v[124:125], v[174:175], v[238:239]
	v_pk_fma_f32 v[244:245], v[122:123], v[172:173], v[244:245]
	v_pk_fma_f32 v[242:243], v[120:121], v[170:171], v[242:243]
	v_pk_add_f32 v[120:121], v[198:199], 1.0 op_sel_hi:[1,0]
	v_pk_add_f32 v[122:123], v[196:197], 1.0 op_sel_hi:[1,0]
	v_pk_add_f32 v[124:125], v[202:203], 1.0 op_sel_hi:[1,0]
	v_pk_add_f32 v[160:161], v[168:169], 1.0 op_sel_hi:[1,0]
	v_pk_add_f32 v[158:159], v[166:167], 1.0 op_sel_hi:[1,0]
	v_pk_add_f32 v[156:157], v[194:195], 1.0 op_sel_hi:[1,0]
	v_pk_add_f32 v[154:155], v[192:193], 1.0 op_sel_hi:[1,0]
	v_pk_fma_f32 v[240:241], v[126:127], v[176:177], v[240:241]
	v_pk_add_f32 v[126:127], v[200:201], 1.0 op_sel_hi:[1,0]
	v_pk_add_f32 v[196:197], v[206:207], 1.0 op_sel_hi:[1,0]
	v_cvt_pk_bf16_f32 v192, v238, v239
	v_cvt_pk_bf16_f32 v193, v240, v241
	v_cvt_pk_bf16_f32 v194, v242, v243
	v_cvt_pk_bf16_f32 v195, v244, v245
	v_pk_mul_f32 v[166:167], v[214:215], v[120:121]
	v_pk_mul_f32 v[168:169], v[212:213], v[122:123]
	v_pk_mul_f32 v[162:163], v[218:219], v[124:125]
	v_pk_add_f32 v[198:199], v[204:205], 1.0 op_sel_hi:[1,0]
	v_pk_mul_f32 v[164:165], v[216:217], v[126:127]
	v_pk_mul_f32 v[126:127], v[222:223], v[196:197]
	global_store_dwordx4 v[234:235], v[192:195], off
	v_pk_mul_f32 v[196:197], v[162:163], v[244:245]
	v_pk_mul_f32 v[124:125], v[220:221], v[198:199]
	v_pk_mul_f32 v[194:195], v[166:167], v[240:241]
	v_pk_mul_f32 v[192:193], v[168:169], v[238:239]
	v_pk_mul_f32 v[198:199], v[164:165], v[242:243]
	v_cvt_pk_bf16_f32 v192, v192, v193
	v_cvt_pk_bf16_f32 v193, v194, v195
	v_mul_f32_e32 v191, v239, v239
	v_cvt_pk_bf16_f32 v194, v198, v199
	v_cvt_pk_bf16_f32 v195, v196, v197
	v_lshl_add_u64 v[196:197], s[10:11], 0, v[232:233]
	global_store_dwordx4 v[196:197], v[192:195], off
	v_fmac_f32_e32 v191, v238, v238
	v_pk_add_f32 v[200:201], v[210:211], 1.0 op_sel_hi:[1,0]
	v_mul_f32_e32 v192, v241, v241
	v_fmac_f32_e32 v192, v240, v240
	v_add_f32_e32 v191, v191, v192
	v_mul_f32_e32 v192, v243, v243
	v_mul_f32_e32 v193, v245, v245
	v_fmac_f32_e32 v192, v242, v242
	v_fmac_f32_e32 v193, v244, v244
	v_add_f32_e32 v192, v192, v193
	v_add_f32_e32 v191, v191, v192
	v_lshlrev_b32_e32 v192, 16, v228
	v_and_b32_e32 v193, 0xffff0000, v228
	v_lshlrev_b32_e32 v194, 16, v229
	v_and_b32_e32 v195, 0xffff0000, v229
	v_lshlrev_b32_e32 v198, 16, v230
	v_and_b32_e32 v199, 0xffff0000, v230
	v_pk_mul_f32 v[120:121], v[226:227], v[200:201]
	v_lshlrev_b32_e32 v200, 16, v231
	v_and_b32_e32 v201, 0xffff0000, v231
	v_pk_fma_f32 v[118:119], v[118:119], v[160:161], v[194:195]
	v_pk_fma_f32 v[116:117], v[116:117], v[158:159], v[192:193]
	v_pk_fma_f32 v[194:195], v[112:113], v[154:155], v[198:199]
	v_cvt_pk_bf16_f32 v112, v116, v117
	v_cvt_pk_bf16_f32 v113, v118, v119
	v_pk_fma_f32 v[192:193], v[114:115], v[156:157], v[200:201]
	v_cvt_pk_bf16_f32 v114, v194, v195
	v_pk_add_f32 v[202:203], v[208:209], 1.0 op_sel_hi:[1,0]
	v_cvt_pk_bf16_f32 v115, v192, v193
	global_store_dwordx4 v[234:235], v[112:115], off offset:256
	v_pk_mul_f32 v[122:123], v[224:225], v[202:203]
	v_pk_mul_f32 v[198:199], v[126:127], v[118:119]
	v_mul_f32_e32 v112, v117, v117
	v_mul_f32_e32 v113, v119, v119
	v_fmac_f32_e32 v112, v116, v116
	v_fmac_f32_e32 v113, v118, v118
	v_add_f32_e32 v112, v112, v113
	v_mul_f32_e32 v113, v195, v195
	v_mul_f32_e32 v114, v193, v193
	v_fmac_f32_e32 v113, v194, v194
	v_fmac_f32_e32 v114, v192, v192
	v_add_f32_e32 v113, v113, v114
	v_add_f32_e32 v112, v112, v113
	v_and_b32_e32 v114, 64, v190
	v_add_f32_e32 v113, v191, v112
	v_xor_b32_e32 v112, 16, v190
	v_add_u32_e32 v191, 64, v114
	v_cmp_lt_i32_e32 vcc, v112, v191
	v_pk_mul_f32 v[114:115], v[124:125], v[116:117]
	v_pk_mul_f32 v[118:119], v[122:123], v[194:195]
	v_cndmask_b32_e32 v112, v190, v112, vcc
	v_lshlrev_b32_e32 v112, 2, v112
	ds_bpermute_b32 v200, v112, v113
	v_cvt_pk_bf16_f32 v116, v114, v115
	v_pk_mul_f32 v[192:193], v[120:121], v[192:193]
	v_cvt_pk_bf16_f32 v117, v198, v199
	v_cvt_pk_bf16_f32 v118, v118, v119
	s_waitcnt lgkmcnt(0)
	v_add_f32_e32 v114, v113, v200
	v_xor_b32_e32 v113, 32, v190
	v_cmp_lt_i32_e32 vcc, v113, v191
	v_cvt_pk_bf16_f32 v119, v192, v193
	global_store_dwordx4 v[196:197], v[116:119], off offset:256
	s_nop 0
	v_cndmask_b32_e32 v113, v190, v113, vcc
	v_lshlrev_b32_e32 v113, 2, v113
	ds_bpermute_b32 v115, v113, v114
	s_and_saveexec_b64 s[28:29], s[0:1]
	s_cbranch_execz .LBB0_1031
	v_lshl_add_u64 v[116:117], v[180:181], 2, s[14:15]
	s_waitcnt lgkmcnt(0)
	v_add_f32_e32 v114, v114, v115
	ds_write_b32 v246, v114
.LBB0_1031:
	s_or_b64 exec, exec, s[28:29]
	s_waitcnt lgkmcnt(0)
	v_lshlrev_b64 v[114:115], 10, v[182:183]
	v_lshl_add_u64 v[114:115], v[114:115], 0, v[152:153]
	v_lshlrev_b32_e32 v116, 16, v132
	v_and_b32_e32 v117, 0xffff0000, v132
	v_lshlrev_b32_e32 v118, 16, v133
	v_and_b32_e32 v119, 0xffff0000, v133
	v_lshlrev_b32_e32 v132, 16, v134
	v_and_b32_e32 v133, 0xffff0000, v134
	v_lshlrev_b64 v[114:115], 1, v[114:115]
	v_lshlrev_b32_e32 v134, 16, v135
	v_and_b32_e32 v135, 0xffff0000, v135
	v_pk_fma_f32 v[110:111], v[110:111], v[176:177], v[118:119]
	v_pk_fma_f32 v[108:109], v[108:109], v[174:175], v[116:117]
	v_pk_fma_f32 v[118:119], v[104:105], v[170:171], v[132:133]
	v_cvt_pk_bf16_f32 v104, v108, v109
	v_cvt_pk_bf16_f32 v105, v110, v111
	v_lshl_add_u64 v[132:133], s[94:95], 0, v[114:115]
	v_pk_fma_f32 v[116:117], v[106:107], v[172:173], v[134:135]
	v_cvt_pk_bf16_f32 v106, v118, v119
	v_lshl_add_u64 v[114:115], s[10:11], 0, v[114:115]
	v_cvt_pk_bf16_f32 v107, v116, v117
	global_store_dwordx4 v[132:133], v[104:107], off
	v_pk_mul_f32 v[134:135], v[162:163], v[116:117]
	v_pk_mul_f32 v[192:193], v[164:165], v[118:119]
	v_pk_mul_f32 v[104:105], v[168:169], v[108:109]
	v_pk_mul_f32 v[106:107], v[166:167], v[110:111]
	v_cvt_pk_bf16_f32 v104, v104, v105
	s_nop 0
	v_cvt_pk_bf16_f32 v105, v106, v107
	v_cvt_pk_bf16_f32 v106, v192, v193
	v_cvt_pk_bf16_f32 v107, v134, v135
	global_store_dwordx4 v[114:115], v[104:107], off
	s_nop 1
	v_mul_f32_e32 v104, v109, v109
	v_mul_f32_e32 v105, v111, v111
	v_fmac_f32_e32 v104, v108, v108
	v_fmac_f32_e32 v105, v110, v110
	v_add_f32_e32 v104, v104, v105
	v_mul_f32_e32 v105, v119, v119
	v_mul_f32_e32 v106, v117, v117
	v_fmac_f32_e32 v105, v118, v118
	v_fmac_f32_e32 v106, v116, v116
	v_add_f32_e32 v105, v105, v106
	v_add_f32_e32 v116, v104, v105
	v_lshlrev_b32_e32 v104, 16, v128
	v_and_b32_e32 v105, 0xffff0000, v128
	v_lshlrev_b32_e32 v106, 16, v129
	v_and_b32_e32 v107, 0xffff0000, v129
	v_lshlrev_b32_e32 v108, 16, v130
	v_and_b32_e32 v109, 0xffff0000, v130
	v_lshlrev_b32_e32 v110, 16, v131
	v_and_b32_e32 v111, 0xffff0000, v131
	v_pk_fma_f32 v[102:103], v[102:103], v[160:161], v[106:107]
	v_pk_fma_f32 v[100:101], v[100:101], v[158:159], v[104:105]
	v_pk_fma_f32 v[106:107], v[96:97], v[154:155], v[108:109]
	v_cvt_pk_bf16_f32 v96, v100, v101
	v_cvt_pk_bf16_f32 v97, v102, v103
	v_pk_fma_f32 v[104:105], v[98:99], v[156:157], v[110:111]
	v_cvt_pk_bf16_f32 v98, v106, v107
	v_pk_mul_f32 v[108:109], v[126:127], v[102:103]
	v_cvt_pk_bf16_f32 v99, v104, v105
	global_store_dwordx4 v[132:133], v[96:99], off offset:256
	s_nop 1
	v_mul_f32_e32 v96, v101, v101
	v_mul_f32_e32 v97, v103, v103
	v_fmac_f32_e32 v96, v100, v100
	v_fmac_f32_e32 v97, v102, v102
	v_add_f32_e32 v96, v96, v97
	v_mul_f32_e32 v97, v107, v107
	v_mul_f32_e32 v98, v105, v105
	v_fmac_f32_e32 v97, v106, v106
	v_fmac_f32_e32 v98, v104, v104
	v_add_f32_e32 v97, v97, v98
	v_add_f32_e32 v96, v96, v97
	v_add_f32_e32 v99, v116, v96
	ds_bpermute_b32 v110, v112, v99
	v_pk_mul_f32 v[96:97], v[124:125], v[100:101]
	v_pk_mul_f32 v[100:101], v[122:123], v[106:107]
	v_cvt_pk_bf16_f32 v98, v96, v97
	v_pk_mul_f32 v[102:103], v[120:121], v[104:105]
	s_waitcnt lgkmcnt(0)
	v_add_f32_e32 v96, v99, v110
	ds_bpermute_b32 v97, v113, v96
	v_cvt_pk_bf16_f32 v99, v108, v109
	v_cvt_pk_bf16_f32 v100, v100, v101
	v_cvt_pk_bf16_f32 v101, v102, v103
	global_store_dwordx4 v[114:115], v[98:101], off offset:256
	s_and_saveexec_b64 s[28:29], s[0:1]
	s_cbranch_execz .LBB0_1033
	v_lshl_add_u64 v[98:99], v[182:183], 2, s[14:15]
	s_waitcnt lgkmcnt(0)
	v_add_f32_e32 v96, v96, v97
	ds_write_b32 v246, v96 offset:256
.LBB0_1033:
	s_or_b64 exec, exec, s[28:29]
	v_or_b32_e32 v106, 32, v180
	v_ashrrev_i32_e32 v107, 31, v106
	s_waitcnt lgkmcnt(0)
	v_lshlrev_b64 v[96:97], 11, v[106:107]
	v_lshl_add_u64 v[96:97], v[178:179], 0, v[96:97]
	global_load_dwordx4 v[108:111], v[96:97], off
	global_load_dwordx4 v[114:117], v[96:97], off offset:256
	v_or_b32_e32 v104, 48, v180
	v_ashrrev_i32_e32 v105, 31, v104
	v_lshlrev_b64 v[96:97], 11, v[104:105]
	v_lshlrev_b64 v[98:99], 10, v[106:107]
	v_lshl_add_u64 v[96:97], v[178:179], 0, v[96:97]
	v_lshl_add_u64 v[118:119], v[98:99], 0, v[152:153]
	global_load_dwordx4 v[100:103], v[96:97], off
	s_nop 0
	global_load_dwordx4 v[96:99], v[96:97], off offset:256
	v_lshlrev_b64 v[118:119], 1, v[118:119]
	v_lshl_add_u64 v[128:129], s[94:95], 0, v[118:119]
	v_lshl_add_u64 v[118:119], s[10:11], 0, v[118:119]
	s_waitcnt vmcnt(3)
	v_lshlrev_b32_e32 v130, 16, v108
	v_and_b32_e32 v131, 0xffff0000, v108
	v_lshlrev_b32_e32 v108, 16, v109
	v_and_b32_e32 v109, 0xffff0000, v109
	v_lshlrev_b32_e32 v132, 16, v110
	v_and_b32_e32 v133, 0xffff0000, v110
	v_lshlrev_b32_e32 v110, 16, v111
	v_and_b32_e32 v111, 0xffff0000, v111
	s_waitcnt vmcnt(2)
	v_lshlrev_b32_e32 v134, 16, v114
	v_and_b32_e32 v135, 0xffff0000, v114
	v_lshlrev_b32_e32 v114, 16, v115
	v_and_b32_e32 v115, 0xffff0000, v115
	v_lshlrev_b32_e32 v182, 16, v116
	v_and_b32_e32 v183, 0xffff0000, v116
	v_lshlrev_b32_e32 v116, 16, v117
	v_and_b32_e32 v117, 0xffff0000, v117
	v_pk_fma_f32 v[94:95], v[94:95], v[176:177], v[108:109]
	v_pk_fma_f32 v[92:93], v[92:93], v[174:175], v[130:131]
	v_pk_fma_f32 v[90:91], v[90:91], v[172:173], v[110:111]
	v_pk_fma_f32 v[88:89], v[88:89], v[170:171], v[132:133]
	v_pk_fma_f32 v[86:87], v[86:87], v[160:161], v[114:115]
	v_pk_fma_f32 v[84:85], v[84:85], v[158:159], v[134:135]
	v_pk_fma_f32 v[108:109], v[82:83], v[156:157], v[116:117]
	v_pk_fma_f32 v[110:111], v[80:81], v[154:155], v[182:183]
	v_cvt_pk_bf16_f32 v80, v92, v93
	v_cvt_pk_bf16_f32 v81, v94, v95
	v_cvt_pk_bf16_f32 v82, v88, v89
	v_cvt_pk_bf16_f32 v83, v90, v91
	v_pk_mul_f32 v[114:115], v[166:167], v[94:95]
	v_pk_mul_f32 v[116:117], v[168:169], v[92:93]
	v_pk_mul_f32 v[130:131], v[162:163], v[90:91]
	v_pk_mul_f32 v[132:133], v[164:165], v[88:89]
	v_mul_f32_e32 v93, v93, v93
	v_mul_f32_e32 v95, v95, v95
	v_mul_f32_e32 v89, v89, v89
	v_mul_f32_e32 v91, v91, v91
	v_mul_f32_e32 v181, v85, v85
	v_mul_f32_e32 v182, v87, v87
	v_mul_f32_e32 v183, v111, v111
	v_mul_f32_e32 v191, v109, v109
	global_store_dwordx4 v[128:129], v[80:83], off
	v_fmac_f32_e32 v93, v92, v92
	v_fmac_f32_e32 v95, v94, v94
	v_cvt_pk_bf16_f32 v80, v116, v117
	v_cvt_pk_bf16_f32 v81, v114, v115
	v_fmac_f32_e32 v89, v88, v88
	v_fmac_f32_e32 v91, v90, v90
	v_fmac_f32_e32 v181, v84, v84
	v_fmac_f32_e32 v182, v86, v86
	v_fmac_f32_e32 v183, v110, v110
	v_fmac_f32_e32 v191, v108, v108
	v_pk_mul_f32 v[134:135], v[126:127], v[86:87]
	v_cvt_pk_bf16_f32 v82, v132, v133
	v_cvt_pk_bf16_f32 v83, v130, v131
	global_store_dwordx4 v[118:119], v[80:83], off
	v_add_f32_e32 v88, v93, v95
	v_add_f32_e32 v89, v89, v91
	v_cvt_pk_bf16_f32 v80, v84, v85
	v_cvt_pk_bf16_f32 v81, v86, v87
	v_add_f32_e32 v86, v181, v182
	v_add_f32_e32 v87, v183, v191
	v_cvt_pk_bf16_f32 v82, v110, v111
	v_cvt_pk_bf16_f32 v83, v108, v109
	v_add_f32_e32 v88, v88, v89
	global_store_dwordx4 v[128:129], v[80:83], off offset:256
	s_nop 1
	v_add_f32_e32 v80, v86, v87
	v_add_f32_e32 v83, v88, v80
	ds_bpermute_b32 v88, v112, v83
	v_pk_mul_f32 v[80:81], v[124:125], v[84:85]
	v_pk_mul_f32 v[84:85], v[122:123], v[110:111]
	v_cvt_pk_bf16_f32 v82, v80, v81
	v_pk_mul_f32 v[86:87], v[120:121], v[108:109]
	s_waitcnt lgkmcnt(0)
	v_add_f32_e32 v80, v83, v88
	ds_bpermute_b32 v81, v113, v80
	v_cvt_pk_bf16_f32 v83, v134, v135
	v_cvt_pk_bf16_f32 v84, v84, v85
	v_cvt_pk_bf16_f32 v85, v86, v87
	global_store_dwordx4 v[118:119], v[82:85], off offset:256
	s_and_saveexec_b64 s[28:29], s[0:1]
	s_cbranch_execz .LBB0_1035
	v_lshl_add_u64 v[82:83], v[106:107], 2, s[14:15]
	s_waitcnt lgkmcnt(0)
	v_add_f32_e32 v80, v80, v81
	ds_write_b32 v246, v80 offset:512
.LBB0_1035:
	s_or_b64 exec, exec, s[28:29]
	s_waitcnt lgkmcnt(0)
	v_lshlrev_b64 v[80:81], 10, v[104:105]
	v_lshl_add_u64 v[80:81], v[80:81], 0, v[152:153]
	s_waitcnt vmcnt(5)
	v_lshlrev_b32_e32 v82, 16, v100
	v_and_b32_e32 v83, 0xffff0000, v100
	v_lshlrev_b32_e32 v84, 16, v101
	v_and_b32_e32 v85, 0xffff0000, v101
	v_lshlrev_b32_e32 v86, 16, v102
	v_and_b32_e32 v87, 0xffff0000, v102
	v_lshlrev_b64 v[80:81], 1, v[80:81]
	v_lshlrev_b32_e32 v88, 16, v103
	v_and_b32_e32 v89, 0xffff0000, v103
	v_pk_fma_f32 v[78:79], v[78:79], v[176:177], v[84:85]
	v_pk_fma_f32 v[76:77], v[76:77], v[174:175], v[82:83]
	v_pk_fma_f32 v[84:85], v[72:73], v[170:171], v[86:87]
	v_cvt_pk_bf16_f32 v72, v76, v77
	v_cvt_pk_bf16_f32 v73, v78, v79
	v_lshl_add_u64 v[86:87], s[94:95], 0, v[80:81]
	v_pk_fma_f32 v[82:83], v[74:75], v[172:173], v[88:89]
	v_cvt_pk_bf16_f32 v74, v84, v85
	v_lshl_add_u64 v[80:81], s[10:11], 0, v[80:81]
	v_cvt_pk_bf16_f32 v75, v82, v83
	global_store_dwordx4 v[86:87], v[72:75], off
	v_pk_mul_f32 v[88:89], v[162:163], v[82:83]
	v_pk_mul_f32 v[90:91], v[164:165], v[84:85]
	v_pk_mul_f32 v[72:73], v[168:169], v[76:77]
	v_pk_mul_f32 v[74:75], v[166:167], v[78:79]
	v_cvt_pk_bf16_f32 v72, v72, v73
	s_nop 0
	v_cvt_pk_bf16_f32 v73, v74, v75
	v_cvt_pk_bf16_f32 v74, v90, v91
	v_cvt_pk_bf16_f32 v75, v88, v89
	global_store_dwordx4 v[80:81], v[72:75], off
	s_nop 1
	v_mul_f32_e32 v72, v77, v77
	v_mul_f32_e32 v73, v79, v79
	v_fmac_f32_e32 v72, v76, v76
	v_fmac_f32_e32 v73, v78, v78
	v_add_f32_e32 v72, v72, v73
	v_mul_f32_e32 v73, v85, v85
	v_mul_f32_e32 v74, v83, v83
	v_fmac_f32_e32 v73, v84, v84
	v_fmac_f32_e32 v74, v82, v82
	v_add_f32_e32 v73, v73, v74
	v_add_f32_e32 v82, v72, v73
	s_waitcnt vmcnt(6)
	v_lshlrev_b32_e32 v72, 16, v96
	v_and_b32_e32 v73, 0xffff0000, v96
	v_lshlrev_b32_e32 v74, 16, v97
	v_and_b32_e32 v75, 0xffff0000, v97
	v_lshlrev_b32_e32 v76, 16, v98
	v_and_b32_e32 v77, 0xffff0000, v98
	v_lshlrev_b32_e32 v78, 16, v99
	v_and_b32_e32 v79, 0xffff0000, v99
	v_pk_fma_f32 v[70:71], v[70:71], v[160:161], v[74:75]
	v_pk_fma_f32 v[68:69], v[68:69], v[158:159], v[72:73]
	v_pk_fma_f32 v[74:75], v[64:65], v[154:155], v[76:77]
	v_cvt_pk_bf16_f32 v64, v68, v69
	v_cvt_pk_bf16_f32 v65, v70, v71
	v_pk_fma_f32 v[72:73], v[66:67], v[156:157], v[78:79]
	v_cvt_pk_bf16_f32 v66, v74, v75
	v_pk_mul_f32 v[76:77], v[126:127], v[70:71]
	v_cvt_pk_bf16_f32 v67, v72, v73
	global_store_dwordx4 v[86:87], v[64:67], off offset:256
	s_nop 1
	v_mul_f32_e32 v64, v69, v69
	v_mul_f32_e32 v65, v71, v71
	v_fmac_f32_e32 v64, v68, v68
	v_fmac_f32_e32 v65, v70, v70
	v_add_f32_e32 v64, v64, v65
	v_mul_f32_e32 v65, v75, v75
	v_mul_f32_e32 v66, v73, v73
	v_fmac_f32_e32 v65, v74, v74
	v_fmac_f32_e32 v66, v72, v72
	v_add_f32_e32 v65, v65, v66
	v_add_f32_e32 v64, v64, v65
	v_add_f32_e32 v67, v82, v64
	ds_bpermute_b32 v78, v112, v67
	v_pk_mul_f32 v[64:65], v[124:125], v[68:69]
	v_pk_mul_f32 v[68:69], v[122:123], v[74:75]
	v_cvt_pk_bf16_f32 v66, v64, v65
	v_pk_mul_f32 v[70:71], v[120:121], v[72:73]
	s_waitcnt lgkmcnt(0)
	v_add_f32_e32 v64, v67, v78
	ds_bpermute_b32 v65, v113, v64
	v_cvt_pk_bf16_f32 v67, v76, v77
	v_cvt_pk_bf16_f32 v68, v68, v69
	v_cvt_pk_bf16_f32 v69, v70, v71
	global_store_dwordx4 v[80:81], v[66:69], off offset:256
	s_and_saveexec_b64 s[28:29], s[0:1]
	s_cbranch_execz .LBB0_1037
	v_lshl_add_u64 v[66:67], v[104:105], 2, s[14:15]
	s_waitcnt lgkmcnt(0)
	v_add_f32_e32 v64, v64, v65
	ds_write_b32 v246, v64 offset:768
.LBB0_1037:
	s_or_b64 exec, exec, s[28:29]
	v_add_u32_e32 v74, 0x80, v180
	v_ashrrev_i32_e32 v75, 31, v74
	s_waitcnt lgkmcnt(0)
	v_lshlrev_b64 v[64:65], 11, v[74:75]
	v_lshl_add_u64 v[64:65], v[178:179], 0, v[64:65]
	global_load_dwordx4 v[76:79], v[64:65], off
	global_load_dwordx4 v[80:83], v[64:65], off offset:256
	v_add_u32_e32 v72, 0x90, v180
	v_ashrrev_i32_e32 v73, 31, v72
	v_lshlrev_b64 v[64:65], 11, v[72:73]
	v_lshlrev_b64 v[66:67], 10, v[74:75]
	v_lshl_add_u64 v[64:65], v[178:179], 0, v[64:65]
	v_lshl_add_u64 v[84:85], v[66:67], 0, v[152:153]
	global_load_dwordx4 v[68:71], v[64:65], off
	s_nop 0
	global_load_dwordx4 v[64:67], v[64:65], off offset:256
	v_lshlrev_b64 v[84:85], 1, v[84:85]
	v_lshl_add_u64 v[86:87], s[94:95], 0, v[84:85]
	v_lshl_add_u64 v[84:85], s[10:11], 0, v[84:85]
	s_waitcnt vmcnt(3)
	v_lshlrev_b32_e32 v88, 16, v76
	v_and_b32_e32 v89, 0xffff0000, v76
	v_lshlrev_b32_e32 v76, 16, v77
	v_and_b32_e32 v77, 0xffff0000, v77
	v_lshlrev_b32_e32 v90, 16, v78
	v_and_b32_e32 v91, 0xffff0000, v78
	v_lshlrev_b32_e32 v78, 16, v79
	v_and_b32_e32 v79, 0xffff0000, v79
	s_waitcnt vmcnt(2)
	v_lshlrev_b32_e32 v92, 16, v80
	v_and_b32_e32 v93, 0xffff0000, v80
	v_lshlrev_b32_e32 v80, 16, v81
	v_and_b32_e32 v81, 0xffff0000, v81
	v_lshlrev_b32_e32 v94, 16, v82
	v_and_b32_e32 v95, 0xffff0000, v82
	v_lshlrev_b32_e32 v82, 16, v83
	v_and_b32_e32 v83, 0xffff0000, v83
	v_pk_fma_f32 v[62:63], v[62:63], v[176:177], v[76:77]
	v_pk_fma_f32 v[60:61], v[60:61], v[174:175], v[88:89]
	v_pk_fma_f32 v[58:59], v[58:59], v[172:173], v[78:79]
	v_pk_fma_f32 v[56:57], v[56:57], v[170:171], v[90:91]
	v_pk_fma_f32 v[54:55], v[54:55], v[160:161], v[80:81]
	v_pk_fma_f32 v[52:53], v[52:53], v[158:159], v[92:93]
	v_pk_fma_f32 v[76:77], v[50:51], v[156:157], v[82:83]
	v_pk_fma_f32 v[78:79], v[48:49], v[154:155], v[94:95]
	v_cvt_pk_bf16_f32 v48, v60, v61
	v_cvt_pk_bf16_f32 v49, v62, v63
	v_cvt_pk_bf16_f32 v50, v56, v57
	v_cvt_pk_bf16_f32 v51, v58, v59
	v_pk_mul_f32 v[80:81], v[166:167], v[62:63]
	v_pk_mul_f32 v[82:83], v[168:169], v[60:61]
	v_pk_mul_f32 v[88:89], v[162:163], v[58:59]
	v_pk_mul_f32 v[90:91], v[164:165], v[56:57]
	v_mul_f32_e32 v61, v61, v61
	v_mul_f32_e32 v63, v63, v63
	v_mul_f32_e32 v57, v57, v57
	v_mul_f32_e32 v59, v59, v59
	v_mul_f32_e32 v94, v53, v53
	v_mul_f32_e32 v95, v55, v55
	v_mul_f32_e32 v96, v79, v79
	v_mul_f32_e32 v97, v77, v77
	global_store_dwordx4 v[86:87], v[48:51], off
	v_fmac_f32_e32 v61, v60, v60
	v_fmac_f32_e32 v63, v62, v62
	v_cvt_pk_bf16_f32 v48, v82, v83
	v_cvt_pk_bf16_f32 v49, v80, v81
	v_fmac_f32_e32 v57, v56, v56
	v_fmac_f32_e32 v59, v58, v58
	v_fmac_f32_e32 v94, v52, v52
	v_fmac_f32_e32 v95, v54, v54
	v_fmac_f32_e32 v96, v78, v78
	v_fmac_f32_e32 v97, v76, v76
	v_pk_mul_f32 v[92:93], v[126:127], v[54:55]
	v_cvt_pk_bf16_f32 v50, v90, v91
	v_cvt_pk_bf16_f32 v51, v88, v89
	global_store_dwordx4 v[84:85], v[48:51], off
	v_add_f32_e32 v56, v61, v63
	v_add_f32_e32 v57, v57, v59
	v_cvt_pk_bf16_f32 v48, v52, v53
	v_cvt_pk_bf16_f32 v49, v54, v55
	v_add_f32_e32 v54, v94, v95
	v_add_f32_e32 v55, v96, v97
	v_cvt_pk_bf16_f32 v50, v78, v79
	v_cvt_pk_bf16_f32 v51, v76, v77
	v_add_f32_e32 v56, v56, v57
	global_store_dwordx4 v[86:87], v[48:51], off offset:256
	s_nop 1
	v_add_f32_e32 v48, v54, v55
	v_add_f32_e32 v51, v56, v48
	ds_bpermute_b32 v56, v112, v51
	v_pk_mul_f32 v[48:49], v[124:125], v[52:53]
	v_pk_mul_f32 v[52:53], v[122:123], v[78:79]
	v_cvt_pk_bf16_f32 v50, v48, v49
	v_pk_mul_f32 v[54:55], v[120:121], v[76:77]
	s_waitcnt lgkmcnt(0)
	v_add_f32_e32 v48, v51, v56
	ds_bpermute_b32 v49, v113, v48
	v_cvt_pk_bf16_f32 v51, v92, v93
	v_cvt_pk_bf16_f32 v52, v52, v53
	v_cvt_pk_bf16_f32 v53, v54, v55
	global_store_dwordx4 v[84:85], v[50:53], off offset:256
	s_and_saveexec_b64 s[28:29], s[0:1]
	s_cbranch_execz .LBB0_1039
	v_lshl_add_u64 v[50:51], v[74:75], 2, s[14:15]
	s_waitcnt lgkmcnt(0)
	v_add_f32_e32 v48, v48, v49
	ds_write_b32 v246, v48 offset:2048
.LBB0_1039:
	s_or_b64 exec, exec, s[28:29]
	s_waitcnt lgkmcnt(0)
	v_lshlrev_b64 v[48:49], 10, v[72:73]
	v_lshl_add_u64 v[48:49], v[48:49], 0, v[152:153]
	s_waitcnt vmcnt(5)
	v_lshlrev_b32_e32 v50, 16, v68
	v_and_b32_e32 v51, 0xffff0000, v68
	v_lshlrev_b32_e32 v52, 16, v69
	v_and_b32_e32 v53, 0xffff0000, v69
	v_lshlrev_b32_e32 v54, 16, v70
	v_and_b32_e32 v55, 0xffff0000, v70
	v_lshlrev_b64 v[48:49], 1, v[48:49]
	v_lshlrev_b32_e32 v56, 16, v71
	v_and_b32_e32 v57, 0xffff0000, v71
	v_pk_fma_f32 v[46:47], v[46:47], v[176:177], v[52:53]
	v_pk_fma_f32 v[44:45], v[44:45], v[174:175], v[50:51]
	v_pk_fma_f32 v[52:53], v[40:41], v[170:171], v[54:55]
	v_cvt_pk_bf16_f32 v40, v44, v45
	v_cvt_pk_bf16_f32 v41, v46, v47
	v_lshl_add_u64 v[54:55], s[94:95], 0, v[48:49]
	v_pk_fma_f32 v[50:51], v[42:43], v[172:173], v[56:57]
	v_cvt_pk_bf16_f32 v42, v52, v53
	v_lshl_add_u64 v[48:49], s[10:11], 0, v[48:49]
	v_cvt_pk_bf16_f32 v43, v50, v51
	global_store_dwordx4 v[54:55], v[40:43], off
	v_pk_mul_f32 v[56:57], v[162:163], v[50:51]
	v_pk_mul_f32 v[58:59], v[164:165], v[52:53]
	v_pk_mul_f32 v[40:41], v[168:169], v[44:45]
	v_pk_mul_f32 v[42:43], v[166:167], v[46:47]
	v_cvt_pk_bf16_f32 v40, v40, v41
	s_nop 0
	v_cvt_pk_bf16_f32 v41, v42, v43
	v_cvt_pk_bf16_f32 v42, v58, v59
	v_cvt_pk_bf16_f32 v43, v56, v57
	global_store_dwordx4 v[48:49], v[40:43], off
	s_nop 1
	v_mul_f32_e32 v40, v45, v45
	v_mul_f32_e32 v41, v47, v47
	v_fmac_f32_e32 v40, v44, v44
	v_fmac_f32_e32 v41, v46, v46
	v_add_f32_e32 v40, v40, v41
	v_mul_f32_e32 v41, v53, v53
	v_mul_f32_e32 v42, v51, v51
	v_fmac_f32_e32 v41, v52, v52
	v_fmac_f32_e32 v42, v50, v50
	v_add_f32_e32 v41, v41, v42
	v_add_f32_e32 v50, v40, v41
	s_waitcnt vmcnt(6)
	v_lshlrev_b32_e32 v40, 16, v64
	v_and_b32_e32 v41, 0xffff0000, v64
	v_lshlrev_b32_e32 v42, 16, v65
	v_and_b32_e32 v43, 0xffff0000, v65
	v_lshlrev_b32_e32 v44, 16, v66
	v_and_b32_e32 v45, 0xffff0000, v66
	v_lshlrev_b32_e32 v46, 16, v67
	v_and_b32_e32 v47, 0xffff0000, v67
	v_pk_fma_f32 v[38:39], v[38:39], v[160:161], v[42:43]
	v_pk_fma_f32 v[36:37], v[36:37], v[158:159], v[40:41]
	v_pk_fma_f32 v[42:43], v[32:33], v[154:155], v[44:45]
	v_cvt_pk_bf16_f32 v32, v36, v37
	v_cvt_pk_bf16_f32 v33, v38, v39
	v_pk_fma_f32 v[40:41], v[34:35], v[156:157], v[46:47]
	v_cvt_pk_bf16_f32 v34, v42, v43
	v_pk_mul_f32 v[44:45], v[126:127], v[38:39]
	v_cvt_pk_bf16_f32 v35, v40, v41
	global_store_dwordx4 v[54:55], v[32:35], off offset:256
	s_nop 1
	v_mul_f32_e32 v32, v37, v37
	v_mul_f32_e32 v33, v39, v39
	v_fmac_f32_e32 v32, v36, v36
	v_fmac_f32_e32 v33, v38, v38
	v_add_f32_e32 v32, v32, v33
	v_mul_f32_e32 v33, v43, v43
	v_mul_f32_e32 v34, v41, v41
	v_fmac_f32_e32 v33, v42, v42
	v_fmac_f32_e32 v34, v40, v40
	v_add_f32_e32 v33, v33, v34
	v_add_f32_e32 v32, v32, v33
	v_add_f32_e32 v35, v50, v32
	ds_bpermute_b32 v46, v112, v35
	v_pk_mul_f32 v[32:33], v[124:125], v[36:37]
	v_pk_mul_f32 v[36:37], v[122:123], v[42:43]
	v_cvt_pk_bf16_f32 v34, v32, v33
	v_pk_mul_f32 v[38:39], v[120:121], v[40:41]
	s_waitcnt lgkmcnt(0)
	v_add_f32_e32 v32, v35, v46
	ds_bpermute_b32 v33, v113, v32
	v_cvt_pk_bf16_f32 v35, v44, v45
	v_cvt_pk_bf16_f32 v36, v36, v37
	v_cvt_pk_bf16_f32 v37, v38, v39
	global_store_dwordx4 v[48:49], v[34:37], off offset:256
	s_and_saveexec_b64 s[28:29], s[0:1]
	s_cbranch_execz .LBB0_1041
	v_lshl_add_u64 v[34:35], v[72:73], 2, s[14:15]
	s_waitcnt lgkmcnt(0)
	v_add_f32_e32 v32, v32, v33
	ds_write_b32 v246, v32 offset:2304
.LBB0_1041:
	s_or_b64 exec, exec, s[28:29]
	v_add_u32_e32 v42, 0xa0, v180
	v_ashrrev_i32_e32 v43, 31, v42
	s_waitcnt lgkmcnt(0)
	v_lshlrev_b64 v[32:33], 11, v[42:43]
	v_lshl_add_u64 v[32:33], v[178:179], 0, v[32:33]
	global_load_dwordx4 v[44:47], v[32:33], off
	global_load_dwordx4 v[48:51], v[32:33], off offset:256
	v_add_u32_e32 v40, 0xb0, v180
	v_ashrrev_i32_e32 v41, 31, v40
	v_lshlrev_b64 v[32:33], 11, v[40:41]
	v_lshlrev_b64 v[34:35], 10, v[42:43]
	v_lshl_add_u64 v[32:33], v[178:179], 0, v[32:33]
	v_lshl_add_u64 v[52:53], v[34:35], 0, v[152:153]
	global_load_dwordx4 v[36:39], v[32:33], off
	s_nop 0
	global_load_dwordx4 v[32:35], v[32:33], off offset:256
	v_lshlrev_b64 v[52:53], 1, v[52:53]
	v_lshl_add_u64 v[54:55], s[94:95], 0, v[52:53]
	v_lshl_add_u64 v[52:53], s[10:11], 0, v[52:53]
	s_waitcnt vmcnt(3)
	v_lshlrev_b32_e32 v56, 16, v44
	v_and_b32_e32 v57, 0xffff0000, v44
	v_lshlrev_b32_e32 v44, 16, v45
	v_and_b32_e32 v45, 0xffff0000, v45
	v_lshlrev_b32_e32 v58, 16, v46
	v_and_b32_e32 v59, 0xffff0000, v46
	v_lshlrev_b32_e32 v46, 16, v47
	v_and_b32_e32 v47, 0xffff0000, v47
	s_waitcnt vmcnt(2)
	v_lshlrev_b32_e32 v60, 16, v48
	v_and_b32_e32 v61, 0xffff0000, v48
	v_lshlrev_b32_e32 v48, 16, v49
	v_and_b32_e32 v49, 0xffff0000, v49
	v_lshlrev_b32_e32 v62, 16, v50
	v_and_b32_e32 v63, 0xffff0000, v50
	v_lshlrev_b32_e32 v50, 16, v51
	v_and_b32_e32 v51, 0xffff0000, v51
	v_pk_fma_f32 v[30:31], v[30:31], v[176:177], v[44:45]
	v_pk_fma_f32 v[28:29], v[28:29], v[174:175], v[56:57]
	v_pk_fma_f32 v[26:27], v[26:27], v[172:173], v[46:47]
	v_pk_fma_f32 v[24:25], v[24:25], v[170:171], v[58:59]
	v_pk_fma_f32 v[22:23], v[22:23], v[160:161], v[48:49]
	v_pk_fma_f32 v[20:21], v[20:21], v[158:159], v[60:61]
	v_pk_fma_f32 v[44:45], v[18:19], v[156:157], v[50:51]
	v_pk_fma_f32 v[46:47], v[16:17], v[154:155], v[62:63]
	v_cvt_pk_bf16_f32 v16, v28, v29
	v_cvt_pk_bf16_f32 v17, v30, v31
	v_cvt_pk_bf16_f32 v18, v24, v25
	v_cvt_pk_bf16_f32 v19, v26, v27
	v_pk_mul_f32 v[48:49], v[166:167], v[30:31]
	v_pk_mul_f32 v[50:51], v[168:169], v[28:29]
	v_pk_mul_f32 v[56:57], v[162:163], v[26:27]
	v_pk_mul_f32 v[58:59], v[164:165], v[24:25]
	v_mul_f32_e32 v29, v29, v29
	v_mul_f32_e32 v31, v31, v31
	v_mul_f32_e32 v25, v25, v25
	v_mul_f32_e32 v27, v27, v27
	v_mul_f32_e32 v62, v21, v21
	v_mul_f32_e32 v63, v23, v23
	v_mul_f32_e32 v64, v47, v47
	v_mul_f32_e32 v65, v45, v45
	global_store_dwordx4 v[54:55], v[16:19], off
	v_fmac_f32_e32 v29, v28, v28
	v_fmac_f32_e32 v31, v30, v30
	v_cvt_pk_bf16_f32 v16, v50, v51
	v_cvt_pk_bf16_f32 v17, v48, v49
	v_fmac_f32_e32 v25, v24, v24
	v_fmac_f32_e32 v27, v26, v26
	v_fmac_f32_e32 v62, v20, v20
	v_fmac_f32_e32 v63, v22, v22
	v_fmac_f32_e32 v64, v46, v46
	v_fmac_f32_e32 v65, v44, v44
	v_pk_mul_f32 v[60:61], v[126:127], v[22:23]
	v_cvt_pk_bf16_f32 v18, v58, v59
	v_cvt_pk_bf16_f32 v19, v56, v57
	global_store_dwordx4 v[52:53], v[16:19], off
	v_add_f32_e32 v24, v29, v31
	v_add_f32_e32 v25, v25, v27
	v_cvt_pk_bf16_f32 v16, v20, v21
	v_cvt_pk_bf16_f32 v17, v22, v23
	v_add_f32_e32 v22, v62, v63
	v_add_f32_e32 v23, v64, v65
	v_cvt_pk_bf16_f32 v18, v46, v47
	v_cvt_pk_bf16_f32 v19, v44, v45
	v_add_f32_e32 v24, v24, v25
	global_store_dwordx4 v[54:55], v[16:19], off offset:256
	s_nop 1
	v_add_f32_e32 v16, v22, v23
	v_add_f32_e32 v19, v24, v16
	ds_bpermute_b32 v24, v112, v19
	v_pk_mul_f32 v[16:17], v[124:125], v[20:21]
	v_pk_mul_f32 v[20:21], v[122:123], v[46:47]
	v_cvt_pk_bf16_f32 v18, v16, v17
	v_pk_mul_f32 v[22:23], v[120:121], v[44:45]
	s_waitcnt lgkmcnt(0)
	v_add_f32_e32 v16, v19, v24
	ds_bpermute_b32 v17, v113, v16
	v_cvt_pk_bf16_f32 v19, v60, v61
	v_cvt_pk_bf16_f32 v20, v20, v21
	v_cvt_pk_bf16_f32 v21, v22, v23
	global_store_dwordx4 v[52:53], v[18:21], off offset:256
	s_and_saveexec_b64 s[28:29], s[0:1]
	s_cbranch_execz .LBB0_1043
	v_lshl_add_u64 v[18:19], v[42:43], 2, s[14:15]
	s_waitcnt lgkmcnt(0)
	v_add_f32_e32 v16, v16, v17
	ds_write_b32 v246, v16 offset:2560
.LBB0_1043:
	s_or_b64 exec, exec, s[28:29]
	s_waitcnt lgkmcnt(0)
	v_lshlrev_b64 v[16:17], 10, v[40:41]
	v_lshl_add_u64 v[16:17], v[16:17], 0, v[152:153]
	s_waitcnt vmcnt(5)
	v_lshlrev_b32_e32 v18, 16, v36
	v_and_b32_e32 v19, 0xffff0000, v36
	v_lshlrev_b32_e32 v20, 16, v37
	v_and_b32_e32 v21, 0xffff0000, v37
	v_lshlrev_b32_e32 v22, 16, v38
	v_and_b32_e32 v23, 0xffff0000, v38
	v_lshlrev_b64 v[16:17], 1, v[16:17]
	v_lshlrev_b32_e32 v24, 16, v39
	v_and_b32_e32 v25, 0xffff0000, v39
	v_pk_fma_f32 v[14:15], v[14:15], v[176:177], v[20:21]
	v_pk_fma_f32 v[12:13], v[12:13], v[174:175], v[18:19]
	v_pk_fma_f32 v[20:21], v[8:9], v[170:171], v[22:23]
	v_cvt_pk_bf16_f32 v8, v12, v13
	v_cvt_pk_bf16_f32 v9, v14, v15
	v_lshl_add_u64 v[22:23], s[94:95], 0, v[16:17]
	v_pk_fma_f32 v[18:19], v[10:11], v[172:173], v[24:25]
	v_cvt_pk_bf16_f32 v10, v20, v21
	v_lshl_add_u64 v[16:17], s[10:11], 0, v[16:17]
	v_cvt_pk_bf16_f32 v11, v18, v19
	global_store_dwordx4 v[22:23], v[8:11], off
	v_pk_mul_f32 v[24:25], v[162:163], v[18:19]
	v_pk_mul_f32 v[26:27], v[164:165], v[20:21]
	v_pk_mul_f32 v[8:9], v[168:169], v[12:13]
	v_pk_mul_f32 v[10:11], v[166:167], v[14:15]
	v_cvt_pk_bf16_f32 v8, v8, v9
	s_nop 0
	v_cvt_pk_bf16_f32 v9, v10, v11
	v_cvt_pk_bf16_f32 v10, v26, v27
	v_cvt_pk_bf16_f32 v11, v24, v25
	global_store_dwordx4 v[16:17], v[8:11], off
	s_nop 1
	v_mul_f32_e32 v8, v13, v13
	v_mul_f32_e32 v9, v15, v15
	v_fmac_f32_e32 v8, v12, v12
	v_fmac_f32_e32 v9, v14, v14
	v_add_f32_e32 v8, v8, v9
	v_mul_f32_e32 v9, v21, v21
	v_mul_f32_e32 v10, v19, v19
	v_fmac_f32_e32 v9, v20, v20
	v_fmac_f32_e32 v10, v18, v18
	v_add_f32_e32 v9, v9, v10
	v_add_f32_e32 v18, v8, v9
	s_waitcnt vmcnt(6)
	v_lshlrev_b32_e32 v8, 16, v32
	v_and_b32_e32 v9, 0xffff0000, v32
	v_lshlrev_b32_e32 v10, 16, v33
	v_and_b32_e32 v11, 0xffff0000, v33
	v_lshlrev_b32_e32 v12, 16, v34
	v_and_b32_e32 v13, 0xffff0000, v34
	v_lshlrev_b32_e32 v14, 16, v35
	v_and_b32_e32 v15, 0xffff0000, v35
	v_pk_fma_f32 v[6:7], v[6:7], v[160:161], v[10:11]
	v_pk_fma_f32 v[4:5], v[4:5], v[158:159], v[8:9]
	v_pk_fma_f32 v[10:11], v[0:1], v[154:155], v[12:13]
	v_cvt_pk_bf16_f32 v0, v4, v5
	v_cvt_pk_bf16_f32 v1, v6, v7
	v_pk_fma_f32 v[8:9], v[2:3], v[156:157], v[14:15]
	v_cvt_pk_bf16_f32 v2, v10, v11
	v_pk_mul_f32 v[12:13], v[126:127], v[6:7]
	v_cvt_pk_bf16_f32 v3, v8, v9
	global_store_dwordx4 v[22:23], v[0:3], off offset:256
	s_nop 1
	v_mul_f32_e32 v0, v5, v5
	v_mul_f32_e32 v1, v7, v7
	v_fmac_f32_e32 v0, v4, v4
	v_fmac_f32_e32 v1, v6, v6
	v_add_f32_e32 v0, v0, v1
	v_mul_f32_e32 v1, v11, v11
	v_mul_f32_e32 v2, v9, v9
	v_fmac_f32_e32 v1, v10, v10
	v_fmac_f32_e32 v2, v8, v8
	v_add_f32_e32 v1, v1, v2
	v_add_f32_e32 v0, v0, v1
	v_add_f32_e32 v3, v18, v0
	ds_bpermute_b32 v14, v112, v3
	v_pk_mul_f32 v[0:1], v[124:125], v[4:5]
	v_pk_mul_f32 v[4:5], v[122:123], v[10:11]
	v_cvt_pk_bf16_f32 v2, v0, v1
	v_pk_mul_f32 v[6:7], v[120:121], v[8:9]
	s_waitcnt lgkmcnt(0)
	v_add_f32_e32 v0, v3, v14
	ds_bpermute_b32 v1, v113, v0
	v_cvt_pk_bf16_f32 v3, v12, v13
	v_cvt_pk_bf16_f32 v4, v4, v5
	v_cvt_pk_bf16_f32 v5, v6, v7
	global_store_dwordx4 v[16:17], v[2:5], off offset:256
	s_and_saveexec_b64 s[28:29], s[0:1]
	s_cbranch_execz .LBB0_1045
	v_lshl_add_u64 v[2:3], v[40:41], 2, s[14:15]
	s_waitcnt lgkmcnt(0)
	v_add_f32_e32 v0, v0, v1
	ds_write_b32 v246, v0 offset:2816
.LBB0_1045:
	s_or_b64 exec, exec, s[28:29]
	s_waitcnt lgkmcnt(0)
	s_barrier
	v_readfirstlane_b32 s74, v236
	v_readfirstlane_b32 s75, v180
	s_lshr_b32 s74, s74, 1
	s_and_b32 s75, s75, 0xffffff00
	s_add_u32 s75, s75, s74
	v_mbcnt_lo_u32_b32 v2, -1, 0
	v_mbcnt_hi_u32_b32 v2, -1, v2
	v_cmp_gt_u32_e32 vcc, 32, v2
	s_and_saveexec_b64 s[76:77], vcc
	v_add_u32_e32 v3, s74, v2
	v_lshlrev_b32_e32 v3, 4, v3
	v_add_u32_e32 v3, 0x20400, v3
	ds_read_b128 v[4:7], v3
	v_add_u32_e32 v8, s75, v2
	v_mov_b32_e32 v9, 0
	v_lshl_add_u64 v[8:9], v[8:9], 2, s[14:15]
	s_waitcnt lgkmcnt(0)
	v_add_f32_e32 v4, v4, v5
	v_add_f32_e32 v6, v6, v7
	v_add_f32_e32 v4, v4, v6
	global_atomic_add_f32 v[8:9], v4, off
	s_or_b64 exec, exec, s[76:77]
	s_andn2_b64 vcc, exec, s[6:7]
	s_mov_b64 s[6:7], -1
	s_cbranch_vccnz .LBB0_1018
	s_andn2_b64 vcc, exec, s[8:9]
	s_cbranch_vccnz .LBB0_1017
	s_barrier
	s_branch .LBB0_1017
